# phase_o: lnx_g vectors loaded up front; removed the per-store vmcnt(0) drains
# baseline (speedup 1.0000x reference)
; DI float bf_lo(unsigned u) { return __uint_as_float(u << 16); }
; DI float bf_hi(unsigned u) { return __uint_as_float(u & 0xffff0000u); }
; DI void phase_o(const Params& p, int l, int pi_first, int pi_end, int pi_step) {
;     ...
;   for (int pi = pi_first; pi < pi_end; pi += pi_step) {
;     const int cid = pi * 2 + (wave >> 1);
;     const bool isp = cid < NCH_P;
;     int bh, c;
;     if (isp) { bh = cid >> 7; c = cid & 127; } else { const int j = cid - NCH_P; bh = j >> 1; c = j & 1; }
;     const int b = bh >> 3, h = bh & 7;
;     const int tok = (wave & 1) * 16 + l15;
;     const size_t row = (size_t)((isp ? b * 4096 : MP + b * 64) + c * 32 + tok);
;     bf16x8 rt[2], sa[4][2]; u32x2 oi[4], ba[4], gt[4];
; #pragma unroll
;     for (int ks = 0; ks < 2; ++ks) rt[ks] = *(const bf16x8*)(p.cRT + (size_t)cid * 2048 + tok * 64 + ks * 32 + quad * 8);
; #pragma unroll
;     for (int vt = 0; vt < 4; ++vt) {
; #pragma unroll
;       for (int ks = 0; ks < 2; ++ks) sa[vt][ks] = *(const bf16x8*)(p.gS + (size_t)cid * 4096 + (vt * 16 + l15) * 64 + ks * 32 + quad * 8);
;       oi[vt] = *(const u32x2*)(p.cOI + (size_t)cid * 2048 + tok * 64 + vt * 16 + quad * 4);
;       ba[vt] = *(const u32x2*)(p.cBA + (size_t)cid * 2048 + tok * 64 + vt * 16 + quad * 4);
;       gt[vt] = *(const u32x2*)(p.z + row * NZ + C_GR + h * 64 + vt * 16 + quad * 4);
;     }
;     f32x4 ao[4];
; #pragma unroll
;     for (int vt = 0; vt < 4; ++vt) {
;       f32x4 a = (f32x4){bf_lo(oi[vt][0]), bf_hi(oi[vt][0]), bf_lo(oi[vt][1]), bf_hi(oi[vt][1])};
; #pragma unroll
;       for (int ks = 0; ks < 2; ++ks) a = __builtin_amdgcn_mfma_f32_16x16x32_bf16(sa[vt][ks], rt[ks], a, 0, 0, 0);
;       ao[vt] = a;
;     }
;     float sm = 0.f, sq = 0.f;
; #pragma unroll
;     for (int vt = 0; vt < 4; ++vt)
; #pragma unroll
;       for (int e = 0; e < 4; ++e) { sm += ao[vt][e]; sq += ao[vt][e] * ao[vt][e]; }
;     { const float a1 = __shfl_xor(sm, 16), b1 = __shfl_xor(sq, 16); sm += a1; sq += b1; }
;     { const float a1 = __shfl_xor(sm, 32), b1 = __shfl_xor(sq, 32); sm += a1; sq += b1; }
;     const float mean = sm * (1.0f / 64.0f);
;     const float rstd = rsqrtf(fmaxf(sq * (1.0f / 64.0f) - mean * mean, 0.f) + 64e-5f);
.LBB0_667:
	s_add_i32 s2, s0, 0xfffff000
	s_ashr_i32 s1, s0, 7
	s_lshr_b32 s2, s2, 1
	s_cmpk_lt_i32 s0, 0x1000
	s_cselect_b32 s24, s1, s2
	s_ashr_i32 s1, s24, 3
	s_lshl_b32 s2, s1, 12
	s_lshl_b32 s1, s1, 6
	s_addk_i32 s1, 0x4000
	s_cmpk_lt_i32 s0, 0x1000
	s_cselect_b32 s1, s2, s1
	s_and_b32 s2, s0, 0x7f
	s_cmpk_lt_i32 s0, 0x1000
	s_cselect_b32 s2, s2, s20
	s_lshl_b32 s2, s2, 5
	s_add_i32 s1, s1, s2
	v_or_b32_e32 v78, s1, v39
	s_ashr_i32 s1, s0, 31
	s_lshl_b64 s[2:3], s[0:1], 12
	v_lshl_add_u64 v[6:7], v[18:19], 0, s[2:3]
	global_load_dwordx4 v[2:5], v[6:7], off
	global_load_dwordx4 v[48:51], v[6:7], off offset:64
	s_lshl_b64 s[22:23], s[0:1], 13
	s_lshl_b32 s1, s24, 6
	v_mov_b64_e32 v[6:7], s[10:11]
	s_and_b32 s1, s1, 0x1c0
	v_lshl_add_u64 v[14:15], v[20:21], 0, s[2:3]
	v_lshl_add_u64 v[16:17], v[22:23], 0, s[2:3]
	v_mad_i64_i32 v[6:7], s[2:3], v78, s94, v[6:7]
	s_lshl_b32 s96, s1, 1
	v_lshl_add_u64 v[6:7], v[6:7], 0, s[96:97]
	v_lshl_add_u64 v[30:31], v[24:25], 0, s[22:23]
	v_lshl_add_u64 v[28:29], v[6:7], 0, v[0:1]
	global_load_dwordx4 v[6:9], v[30:31], off
	global_load_dwordx4 v[10:13], v[30:31], off offset:64
	global_load_dwordx2 v[36:37], v[14:15], off
	global_load_dwordx2 v[46:47], v[16:17], off
	global_load_dwordx2 v[44:45], v[28:29], off offset:3328
	global_load_dwordx4 v[54:57], v[30:31], off offset:2048
	global_load_dwordx4 v[58:61], v[30:31], off offset:2112
	global_load_dwordx2 v[80:81], v[14:15], off offset:32
	global_load_dwordx2 v[42:43], v[16:17], off offset:32
	global_load_dwordx2 v[40:41], v[28:29], off offset:3360
	v_add_co_u32_e32 v30, vcc, s26, v30
	s_lshl_b32 s2, s1, 2
	s_nop 0
	v_addc_co_u32_e32 v31, vcc, 0, v31, vcc
	global_load_dwordx4 v[62:65], v[30:31], off
	global_load_dwordx4 v[66:69], v[30:31], off offset:64
	global_load_dwordx2 v[82:83], v[14:15], off offset:64
	global_load_dwordx2 v[34:35], v[16:17], off offset:64
	global_load_dwordx2 v[32:33], v[28:29], off offset:3392
	global_load_dwordx4 v[70:73], v[30:31], off offset:2048
	global_load_dwordx4 v[74:77], v[30:31], off offset:2112
	global_load_dwordx2 v[84:85], v[14:15], off offset:96
	s_nop 0
	global_load_dwordx2 v[30:31], v[16:17], off offset:96
	s_nop 0
	global_load_dwordx2 v[28:29], v[28:29], off offset:3424
	s_mov_b32 s3, s97
	v_lshl_add_u64 v[124:125], v[26:27], 0, s[2:3]
	global_load_dwordx4 v[112:115], v[124:125], off
	global_load_dwordx4 v[116:119], v[124:125], off offset:64
	global_load_dwordx4 v[120:123], v[124:125], off offset:128
	global_load_dwordx4 v[214:217], v[124:125], off offset:192
	v_ashrrev_i32_e32 v79, 31, v78
	s_add_i32 s21, s21, s42
	s_add_i32 s0, s0, s25
	s_cmpk_lt_i32 s21, 0x800
	s_waitcnt vmcnt(21)
	v_lshlrev_b32_e32 v14, 16, v36
	v_and_b32_e32 v15, 0xffff0000, v36
	v_lshlrev_b32_e32 v16, 16, v37
	v_and_b32_e32 v17, 0xffff0000, v37
	s_nop 1
	v_mfma_f32_16x16x32_bf16 v[6:9], v[6:9], v[2:5], v[14:17]
	v_mfma_f32_16x16x32_bf16 v[14:17], v[10:13], v[48:51], v[6:9]
	s_waitcnt vmcnt(16)
	s_nop 5
	v_lshlrev_b32_e32 v6, 16, v80
	v_and_b32_e32 v7, 0xffff0000, v80
	v_lshlrev_b32_e32 v8, 16, v81
	v_and_b32_e32 v9, 0xffff0000, v81
	v_add_f32_e32 v36, 0, v14
	v_add_f32_e32 v36, v15, v36
	v_mfma_f32_16x16x32_bf16 v[6:9], v[54:57], v[2:5], v[6:9]
	s_waitcnt vmcnt(6)
	v_lshlrev_b32_e32 v54, 16, v84
	v_and_b32_e32 v55, 0xffff0000, v84
	v_lshlrev_b32_e32 v56, 16, v85
	v_mfma_f32_16x16x32_bf16 v[10:13], v[58:61], v[48:51], v[6:9]
	v_and_b32_e32 v57, 0xffff0000, v85
	v_add_f32_e32 v36, v16, v36
	v_mul_f32_e32 v38, v15, v15
	v_lshlrev_b32_e32 v6, 16, v82
	v_and_b32_e32 v7, 0xffff0000, v82
	v_lshlrev_b32_e32 v8, 16, v83
	v_and_b32_e32 v9, 0xffff0000, v83
	v_add_f32_e32 v36, v17, v36
	v_fmac_f32_e32 v38, v14, v14
	v_mfma_f32_16x16x32_bf16 v[6:9], v[62:65], v[2:5], v[6:9]
	v_mov_b32_e32 v37, v17
	v_fmac_f32_e32 v38, v16, v16
	v_lshlrev_b32_e32 v58, 16, v46
	v_mfma_f32_16x16x32_bf16 v[2:5], v[70:73], v[2:5], v[54:57]
	v_and_b32_e32 v59, 0xffff0000, v46
	v_lshlrev_b32_e32 v46, 16, v47
	v_and_b32_e32 v47, 0xffff0000, v47
	v_mfma_f32_16x16x32_bf16 v[6:9], v[66:69], v[48:51], v[6:9]
	v_mfma_f32_16x16x32_bf16 v[2:5], v[74:77], v[48:51], v[2:5]
	v_add_f32_e32 v48, v10, v36
	v_mov_b32_e32 v36, v10
	v_pk_mul_f32 v[36:37], v[36:37], v[36:37]
	s_nop 0
	v_add_f32_e32 v37, v37, v38
	v_add_f32_e32 v38, v36, v37
	v_add_f32_e32 v36, v11, v48
	v_add_f32_e32 v50, v12, v36
	v_pk_mul_f32 v[36:37], v[12:13], v[12:13]
	v_pk_mul_f32 v[48:49], v[10:11], v[10:11]
	s_nop 0
	v_add_f32_e32 v37, v49, v38
	v_add_f32_e32 v38, v36, v37
	v_add_f32_e32 v36, v13, v50
	v_add_f32_e32 v48, v6, v36
	v_mov_b32_e32 v36, v6
	v_mov_b32_e32 v37, v13
	v_pk_mul_f32 v[36:37], v[36:37], v[36:37]
	s_nop 0
	v_add_f32_e32 v37, v37, v38
	v_add_f32_e32 v38, v36, v37
	v_add_f32_e32 v36, v7, v48
	v_add_f32_e32 v50, v8, v36
	v_pk_mul_f32 v[36:37], v[8:9], v[8:9]
	v_pk_mul_f32 v[48:49], v[6:7], v[6:7]
	s_nop 0
	v_add_f32_e32 v37, v49, v38
	v_add_f32_e32 v38, v36, v37
	v_add_f32_e32 v36, v9, v50
	v_add_f32_e32 v48, v2, v36
	v_mov_b32_e32 v36, v2
	v_mov_b32_e32 v37, v9
	v_pk_mul_f32 v[36:37], v[36:37], v[36:37]
	v_pk_mul_f32 v[50:51], v[2:3], v[2:3]
	v_add_f32_e32 v37, v37, v38
	v_add_f32_e32 v36, v36, v37
	v_add_f32_e32 v36, v51, v36
	v_lshl_add_u64 v[50:51], v[26:27], 0, s[2:3]
	v_add_f32_e32 v37, v3, v48
	v_pk_mul_f32 v[48:49], v[4:5], v[4:5]
	v_add_f32_e32 v37, v4, v37
	v_add_f32_e32 v48, v48, v36
	v_mul_f32_e32 v36, v5, v5
	v_mov_b32_e32 v49, v5
	v_pk_add_f32 v[36:37], v[48:49], v[36:37]
	ds_bpermute_b32 v49, v52, v37
	ds_bpermute_b32 v48, v52, v36
	s_waitcnt lgkmcnt(0)
; DI unsigned pk2(float a, float b) { f32x2 v = {a, b}; bfv2 r = __builtin_convertvector(v, bfv2); return __builtin_bit_cast(unsigned, r); }
; DI float bf_lo(unsigned u) { return __uint_as_float(u << 16); }
; DI float bf_hi(unsigned u) { return __uint_as_float(u & 0xffff0000u); }
; DI void phase_o(const Params& p, int l, int pi_first, int pi_end, int pi_step) {
;     ...
;     { const float a1 = __shfl_xor(sm, 16), b1 = __shfl_xor(sq, 16); sm += a1; sq += b1; }
;     { const float a1 = __shfl_xor(sm, 32), b1 = __shfl_xor(sq, 32); sm += a1; sq += b1; }
;     const float mean = sm * (1.0f / 64.0f);
;     const float rstd = rsqrtf(fmaxf(sq * (1.0f / 64.0f) - mean * mean, 0.f) + 64e-5f);
;     const float* lg = p.lnx_g + l * 512 + h * 64;
; #pragma unroll
;     for (int vt = 0; vt < 4; ++vt) {
;       const int vv = vt * 16 + quad * 4;
;       const f32x4 g4 = *(const f32x4*)(lg + vv);
;       const float y0 = ((ao[vt][0] - mean) * rstd * g4[0] + bf_lo(ba[vt][0])) * bf_lo(gt[vt][0]);
;       const float y1 = ((ao[vt][1] - mean) * rstd * g4[1] + bf_hi(ba[vt][0])) * bf_hi(gt[vt][0]);
;       const float y2 = ((ao[vt][2] - mean) * rstd * g4[2] + bf_lo(ba[vt][1])) * bf_lo(gt[vt][1]);
;       const float y3 = ((ao[vt][3] - mean) * rstd * g4[3] + bf_hi(ba[vt][1])) * bf_hi(gt[vt][1]);
;       u32x2 ov; ov[0] = pk2(y0, y1); ov[1] = pk2(y2, y3);
;       *(u32x2*)(p.o_r + row * 512 + h * 64 + vv) = ov;
;     }
	v_pk_add_f32 v[36:37], v[36:37], v[48:49]
	ds_bpermute_b32 v49, v53, v37
	ds_bpermute_b32 v48, v53, v36
	s_waitcnt lgkmcnt(0)
	v_pk_add_f32 v[36:37], v[36:37], v[48:49]
	s_nop 0
	v_pk_mul_f32 v[36:37], v[36:37], s[44:45] op_sel_hi:[1,0]
	s_nop 0
	v_fma_f32 v38, -v37, v37, v36
	v_max_f32_e32 v38, 0, v38
	v_add_f32_e32 v38, 0x3a27c5ac, v38
	v_cmp_gt_f32_e32 vcc, s34, v38
	v_mul_f32_e32 v48, 0x4b800000, v38
	v_pk_add_f32 v[14:15], v[14:15], v[36:37] op_sel:[0,1] neg_lo:[0,1] neg_hi:[0,1]
	v_cndmask_b32_e32 v38, v38, v48, vcc
	v_rsq_f32_e32 v38, v38
	v_pk_add_f32 v[16:17], v[16:17], v[36:37] op_sel:[0,1] neg_lo:[0,1] neg_hi:[0,1]
	v_pk_add_f32 v[10:11], v[10:11], v[36:37] op_sel:[0,1] neg_lo:[0,1] neg_hi:[0,1]
	v_pk_add_f32 v[12:13], v[12:13], v[36:37] op_sel:[0,1] neg_lo:[0,1] neg_hi:[0,1]
	v_mul_f32_e32 v48, 0x45800000, v38
	v_cndmask_b32_e32 v38, v38, v48, vcc
	v_pk_mul_f32 v[14:15], v[14:15], v[38:39] op_sel_hi:[1,0]
	v_pk_mul_f32 v[16:17], v[16:17], v[38:39] op_sel_hi:[1,0]
	v_lshlrev_b64 v[48:49], 10, v[78:79]
	v_pk_mul_f32 v[10:11], v[10:11], v[38:39] op_sel_hi:[1,0]
	v_pk_mul_f32 v[12:13], v[12:13], v[38:39] op_sel_hi:[1,0]
	v_pk_add_f32 v[6:7], v[6:7], v[36:37] op_sel:[0,1] neg_lo:[0,1] neg_hi:[0,1]
	v_pk_add_f32 v[8:9], v[8:9], v[36:37] op_sel:[0,1] neg_lo:[0,1] neg_hi:[0,1]
	v_pk_mul_f32 v[6:7], v[6:7], v[38:39] op_sel_hi:[1,0]
	v_pk_mul_f32 v[8:9], v[8:9], v[38:39] op_sel_hi:[1,0]
	v_pk_add_f32 v[2:3], v[2:3], v[36:37] op_sel:[0,1] neg_lo:[0,1] neg_hi:[0,1]
	v_pk_add_f32 v[4:5], v[4:5], v[36:37] op_sel:[0,1] neg_lo:[0,1] neg_hi:[0,1]
	v_pk_mul_f32 v[2:3], v[2:3], v[38:39] op_sel_hi:[1,0]
	v_pk_mul_f32 v[4:5], v[4:5], v[38:39] op_sel_hi:[1,0]
	s_waitcnt vmcnt(0)
	v_pk_fma_f32 v[14:15], v[112:113], v[14:15], v[58:59]
	v_lshlrev_b32_e32 v54, 16, v44
	v_and_b32_e32 v55, 0xffff0000, v44
	v_pk_mul_f32 v[14:15], v[14:15], v[54:55]
	v_pk_fma_f32 v[16:17], v[114:115], v[16:17], v[46:47]
	v_lshlrev_b32_e32 v44, 16, v45
	v_and_b32_e32 v45, 0xffff0000, v45
	v_pk_mul_f32 v[44:45], v[16:17], v[44:45]
	v_cvt_pk_bf16_f32 v16, v14, v15
	v_lshl_add_u64 v[14:15], s[52:53], 0, v[48:49]
	v_lshl_add_u64 v[14:15], v[14:15], 0, s[96:97]
	v_cvt_pk_bf16_f32 v17, v44, v45
	v_lshl_add_u64 v[14:15], v[14:15], 0, v[0:1]
	global_store_dwordx2 v[14:15], v[16:17], off
	v_lshlrev_b32_e32 v16, 16, v42
	v_and_b32_e32 v17, 0xffff0000, v42
	v_pk_fma_f32 v[10:11], v[116:117], v[10:11], v[16:17]
	v_lshlrev_b32_e32 v16, 16, v40
	v_and_b32_e32 v17, 0xffff0000, v40
	v_pk_mul_f32 v[10:11], v[10:11], v[16:17]
	v_lshlrev_b32_e32 v16, 16, v43
	v_and_b32_e32 v17, 0xffff0000, v43
	v_pk_fma_f32 v[12:13], v[118:119], v[12:13], v[16:17]
	v_lshlrev_b32_e32 v16, 16, v41
	v_and_b32_e32 v17, 0xffff0000, v41
	v_pk_mul_f32 v[12:13], v[12:13], v[16:17]
	v_cvt_pk_bf16_f32 v10, v10, v11
	v_cvt_pk_bf16_f32 v11, v12, v13
	global_store_dwordx2 v[14:15], v[10:11], off offset:32
	v_lshlrev_b32_e32 v16, 16, v34
	v_and_b32_e32 v17, 0xffff0000, v34
	v_pk_fma_f32 v[6:7], v[120:121], v[6:7], v[16:17]
	v_lshlrev_b32_e32 v10, 16, v32
	v_and_b32_e32 v11, 0xffff0000, v32
	v_pk_mul_f32 v[6:7], v[6:7], v[10:11]
	v_lshlrev_b32_e32 v10, 16, v35
	v_and_b32_e32 v11, 0xffff0000, v35
	v_pk_fma_f32 v[8:9], v[122:123], v[8:9], v[10:11]
	v_lshlrev_b32_e32 v10, 16, v33
	v_and_b32_e32 v11, 0xffff0000, v33
	v_pk_mul_f32 v[8:9], v[8:9], v[10:11]
	v_cvt_pk_bf16_f32 v6, v6, v7
	v_cvt_pk_bf16_f32 v7, v8, v9
	global_store_dwordx2 v[14:15], v[6:7], off offset:64
	v_lshlrev_b32_e32 v10, 16, v30
	v_and_b32_e32 v11, 0xffff0000, v30
	v_pk_fma_f32 v[2:3], v[214:215], v[2:3], v[10:11]
	v_lshlrev_b32_e32 v6, 16, v28
	v_and_b32_e32 v7, 0xffff0000, v28
	v_pk_mul_f32 v[2:3], v[2:3], v[6:7]
	v_lshlrev_b32_e32 v6, 16, v31
	v_and_b32_e32 v7, 0xffff0000, v31
	v_pk_fma_f32 v[4:5], v[216:217], v[4:5], v[6:7]
	v_lshlrev_b32_e32 v6, 16, v29
	v_and_b32_e32 v7, 0xffff0000, v29
	v_pk_mul_f32 v[4:5], v[4:5], v[6:7]
	v_cvt_pk_bf16_f32 v2, v2, v3
	v_cvt_pk_bf16_f32 v3, v4, v5
	global_store_dwordx2 v[14:15], v[2:3], off offset:96
	s_cbranch_scc1 .LBB0_667
